# LRU phase: waves 4..7 at s_setprio 2 so the two waves of a SIMD stagger instead of running in lockstep
# speedup vs baseline: 1.0014x; 1.0014x over previous
.LBB0_909:
	s_cmp_lt_i32 s34, 7
	s_cselect_b64 s[4:5], -1, 0
	s_cmp_gt_i32 s35, 6
	s_cselect_b64 s[6:7], -1, 0
	s_and_b64 s[4:5], s[4:5], s[6:7]
	s_andn2_b64 vcc, exec, s[4:5]
	s_cbranch_vccnz .LBB0_995
	s_mov_b64 s[40:41], s[0:1]
	s_cmpk_gt_i32 s2, 0x2ff
	s_waitcnt vmcnt(0)
	v_mov_b32_e32 v106, v184
	s_cbranch_scc1 .LBB0_941
	s_cmp_lt_u32 s70, 4
	s_cbranch_scc1 .Lp6_prio_lo
	s_setprio 2
